# MLA attention: K/V LDS fragment reads prefetched 5 deep ahead of the MFMA chain (was read-wait-mfma serialized)
# baseline (speedup 1.0000x reference)
.LBB0_642:
	v_sub_f32_e32 v3, v80, v2
	v_exp_f32_e32 v3, v3
	v_sub_f32_e32 v4, v81, v2
	v_exp_f32_e32 v4, v4
	v_sub_f32_e32 v5, v82, v2
	v_exp_f32_e32 v5, v5
	v_sub_f32_e32 v6, v83, v2
	v_exp_f32_e32 v6, v6
	v_sub_f32_e32 v8, v84, v2
	v_add_f32_e32 v7, 0, v3
	v_exp_f32_e32 v8, v8
	v_sub_f32_e32 v9, v85, v2
	v_add_f32_e32 v7, v4, v7
	v_exp_f32_e32 v9, v9
	v_sub_f32_e32 v10, v86, v2
	v_add_f32_e32 v7, v5, v7
	v_exp_f32_e32 v10, v10
	v_sub_f32_e32 v11, v87, v2
	v_add_f32_e32 v7, v6, v7
	v_exp_f32_e32 v11, v11
	v_sub_f32_e32 v12, v88, v2
	v_add_f32_e32 v7, v8, v7
	v_exp_f32_e32 v12, v12
	v_sub_f32_e32 v13, v89, v2
	v_add_f32_e32 v7, v9, v7
	v_exp_f32_e32 v13, v13
	v_sub_f32_e32 v14, v90, v2
	v_add_f32_e32 v7, v10, v7
	v_exp_f32_e32 v14, v14
	v_sub_f32_e32 v15, v91, v2
	v_add_f32_e32 v7, v11, v7
	v_exp_f32_e32 v15, v15
	v_sub_f32_e32 v80, v92, v2
	v_add_f32_e32 v7, v12, v7
	v_exp_f32_e32 v80, v80
	v_sub_f32_e32 v81, v93, v2
	v_add_f32_e32 v7, v13, v7
	v_exp_f32_e32 v81, v81
	v_sub_f32_e32 v82, v94, v2
	v_add_f32_e32 v7, v14, v7
	v_exp_f32_e32 v82, v82
	v_sub_f32_e32 v83, v95, v2
	v_add_f32_e32 v7, v15, v7
	v_exp_f32_e32 v83, v83
	v_add_f32_e32 v7, v80, v7
	v_add_f32_e32 v7, v81, v7
	v_add_f32_e32 v7, v82, v7
	v_add_f32_e32 v84, v83, v7
	v_fmac_f32_e32 v84, v212, v0
	v_cvt_pk_bf16_f32 v4, v3, v4
	v_cvt_pk_bf16_f32 v5, v5, v6
	v_cvt_pk_bf16_f32 v6, v8, v9
	v_cvt_pk_bf16_f32 v7, v10, v11
	v_cvt_pk_bf16_f32 v8, v12, v13
	v_cvt_pk_bf16_f32 v9, v14, v15
	v_cvt_pk_bf16_f32 v10, v80, v81
	v_cvt_pk_bf16_f32 v11, v82, v83
	s_setprio 1
	ds_read_b64 v[12:13], v227 offset:0
	ds_read_b64 v[14:15], v227 offset:16
	ds_read_b64 v[230:231], v227 offset:32
	ds_read_b64 v[232:233], v227 offset:48
	ds_read_b64 v[234:235], v227 offset:4608
	ds_read_b64 v[236:237], v227 offset:4624
	ds_read_b64 v[246:247], v227 offset:4640
	ds_read_b64 v[248:249], v227 offset:4656
	ds_read_b64 v[250:251], v227 offset:9216
	ds_read_b64 v[252:253], v227 offset:9232
	s_waitcnt lgkmcnt(8)
	v_mfma_f32_32x32x16_bf16 v[64:79], v[12:15], v[4:7], v[64:79]
	ds_read_b64 v[12:13], v227 offset:9248
	ds_read_b64 v[14:15], v227 offset:9264
	s_waitcnt lgkmcnt(8)
	v_mfma_f32_32x32x16_bf16 v[64:79], v[230:233], v[8:11], v[64:79]
	ds_read_b64 v[230:231], v227 offset:13824
	ds_read_b64 v[232:233], v227 offset:13840
	s_waitcnt lgkmcnt(8)
	v_mfma_f32_32x32x16_bf16 v[48:63], v[234:237], v[4:7], v[48:63]
	ds_read_b64 v[234:235], v227 offset:13856
	ds_read_b64 v[236:237], v227 offset:13872
	s_waitcnt lgkmcnt(8)
	v_mfma_f32_32x32x16_bf16 v[48:63], v[246:249], v[8:11], v[48:63]
	s_waitcnt lgkmcnt(6)
	v_mfma_f32_32x32x16_bf16 v[32:47], v[250:253], v[4:7], v[32:47]
	s_waitcnt lgkmcnt(4)
	v_mfma_f32_32x32x16_bf16 v[32:47], v[12:15], v[8:11], v[32:47]
	s_waitcnt lgkmcnt(2)
	v_mfma_f32_32x32x16_bf16 v[16:31], v[230:233], v[4:7], v[16:31]
	s_waitcnt lgkmcnt(0)
	v_mfma_f32_32x32x16_bf16 v[16:31], v[234:237], v[8:11], v[16:31]
	s_setprio 0
	v_mov_b32_e32 v229, v2
	v_mov_b32_e32 v212, v84

; #define AT_LOAD(RK, RV, T) { const size_t ko_ = (size_t)(T) * 64 * 192; const int vo_ = (T) * 64; \
;     _Pragma("unroll") for (int i = 0; i < 3; ++i) { const int id = tid + NT * i, row = id / 24, cc = id % 24; RK[i] = *(const u32x4*)(Kg + ko_ + row * 192 + cc * 8); } \
;     _Pragma("unroll") for (int i = 0; i < 2; ++i) RV[i] = *(const u32x4*)(Vg + (size_t)(vrow + 64 * i) * S_ + vo_ + vcc * 8); }
; #define AT_WRITE(RK, RV, ST) { char* dK = smem + (ST) * STG; \
;     _Pragma("unroll") for (int i = 0; i < 3; ++i) { const int id = tid + NT * i, row = id / 24, cc = id % 24; *(u32x4*)(dK + row * 400 + cc * 16) = RK[i]; } \
;     _Pragma("unroll") for (int i = 0; i < 2; ++i) *(u32x4*)(dK + KST + (vrow + 64 * i) * 144 + vcc * 16) = RV[i]; }
; DI void mla_attn_item(const Params& P, int hd, int b, char* smem) {
;     ...
;     AT_WRITE(rk1, rv1, 1);
;     AT_LOAD(rk1, rv1, (kt + 3 < ntl ? kt + 3 : ntl));
;     AT_COMPUTE(0, kt);
.LBB0_644:
	s_add_i32 s2, s60, 5
	s_min_u32 s2, s2, s57
	s_mul_i32 s62, s2, 0x6000
	v_lshl_add_u64 v[2:3], v[188:189], 0, s[62:63]
	v_lshl_add_u64 v[4:5], v[190:191], 1, v[2:3]
	s_waitcnt vmcnt(0)
	ds_write_b128 v217, v[136:139] offset:44032
	ds_write_b128 v218, v[140:143] offset:44032
	ds_write_b128 v219, v[144:147] offset:44032
	ds_write_b128 v226, v[148:151]
	ds_write_b128 v226, v[152:155] offset:9216
	v_lshl_add_u64 v[4:5], v[192:193], 1, v[4:5]
	v_lshl_add_u64 v[6:7], v[194:195], 1, v[2:3]
	v_lshl_add_u64 v[2:3], v[198:199], 1, v[2:3]
	s_lshl_b32 s62, s2, 7
	v_lshl_add_u64 v[6:7], v[196:197], 1, v[6:7]
	flat_load_dwordx4 v[136:139], v[4:5]
	flat_load_dwordx4 v[140:143], v[6:7]
	v_lshl_add_u64 v[2:3], v[200:201], 1, v[2:3]
	v_lshl_add_u64 v[4:5], v[202:203], 0, s[62:63]
	v_lshl_add_u64 v[6:7], v[4:5], 0, v[204:205]
	flat_load_dwordx4 v[144:147], v[2:3]
	flat_load_dwordx4 v[148:151], v[6:7]
	v_lshl_add_u64 v[2:3], v[4:5], 0, v[210:211]
	flat_load_dwordx4 v[152:155], v[2:3]
	v_add_u32_e32 v0, 0xffffffa1, v224
	v_cmp_le_i32_e32 vcc, v0, v213
	s_and_saveexec_b64 s[38:39], vcc
	s_cbranch_execz .LBB0_650
	s_setprio 1
	ds_read_b128 v[2:5], v228
	ds_read_b128 v[230:233], v228 offset:32
	ds_read_b128 v[234:237], v228 offset:64
	ds_read_b128 v[246:249], v228 offset:96
	ds_read_b128 v[250:253], v228 offset:128
	s_waitcnt lgkmcnt(4)
	v_mfma_f32_32x32x16_bf16 v[80:95], v[2:5], v[96:99], 0
	ds_read_b128 v[2:5], v228 offset:160
	s_waitcnt lgkmcnt(4)
	v_mfma_f32_32x32x16_bf16 v[80:95], v[230:233], v[100:103], v[80:95]
	ds_read_b128 v[230:233], v228 offset:192
	s_waitcnt lgkmcnt(4)
	v_mfma_f32_32x32x16_bf16 v[80:95], v[234:237], v[104:107], v[80:95]
	ds_read_b128 v[234:237], v228 offset:224
	s_waitcnt lgkmcnt(4)
	v_mfma_f32_32x32x16_bf16 v[80:95], v[246:249], v[108:111], v[80:95]
	ds_read_b128 v[246:249], v228 offset:256
	s_waitcnt lgkmcnt(4)
	v_mfma_f32_32x32x16_bf16 v[80:95], v[250:253], v[112:115], v[80:95]
	ds_read_b128 v[250:253], v228 offset:288
	s_waitcnt lgkmcnt(4)
	v_mfma_f32_32x32x16_bf16 v[80:95], v[2:5], v[116:119], v[80:95]
	ds_read_b128 v[2:5], v228 offset:320
	s_waitcnt lgkmcnt(4)
	v_mfma_f32_32x32x16_bf16 v[80:95], v[230:233], v[120:123], v[80:95]
	ds_read_b128 v[230:233], v228 offset:352
	s_waitcnt lgkmcnt(4)
	v_mfma_f32_32x32x16_bf16 v[80:95], v[234:237], v[124:127], v[80:95]
	s_waitcnt lgkmcnt(3)
	v_mfma_f32_32x32x16_bf16 v[80:95], v[246:249], v[128:131], v[80:95]
	s_waitcnt lgkmcnt(2)
	v_mfma_f32_32x32x16_bf16 v[80:95], v[250:253], v[176:179], v[80:95]
	s_waitcnt lgkmcnt(1)
	v_mfma_f32_32x32x16_bf16 v[80:95], v[2:5], v[132:135], v[80:95]
	s_waitcnt lgkmcnt(0)
	v_mfma_f32_32x32x16_bf16 v[80:95], v[230:233], v[180:183], v[80:95]
	s_setprio 0
	v_subrev_u32_e32 v0, 64, v224
	v_cmp_gt_i32_e32 vcc, v0, v213
	s_and_saveexec_b64 s[78:79], vcc
	s_cbranch_execz .LBB0_647
	v_add_u32_e32 v0, 64, v225
	s_nop 0
	v_cmp_gt_i32_e64 s[30:31], 26, v0
	v_cmp_gt_i32_e64 s[34:35], 27, v0
	v_cmp_gt_i32_e64 s[28:29], 25, v0
	s_and_b64 s[30:31], s[34:35], s[30:31]
	v_cmp_gt_i32_e64 s[26:27], 24, v0
	s_and_b64 s[28:29], s[30:31], s[28:29]
	v_cmp_gt_i32_e64 s[24:25], 19, v0
	s_and_b64 s[26:27], s[28:29], s[26:27]
	v_cmp_gt_i32_e64 s[22:23], 18, v0
	s_and_b64 s[24:25], s[26:27], s[24:25]
	v_cmp_gt_i32_e64 s[20:21], 17, v0
	s_and_b64 s[22:23], s[24:25], s[22:23]
	v_cmp_gt_i32_e64 s[18:19], 16, v0
	s_and_b64 s[20:21], s[22:23], s[20:21]
	v_cmp_gt_i32_e64 s[16:17], 11, v0
	s_and_b64 s[18:19], s[20:21], s[18:19]
	v_cmp_gt_i32_e64 s[14:15], 10, v0
	s_and_b64 s[16:17], s[18:19], s[16:17]
	v_cmp_gt_i32_e64 s[12:13], 9, v0
	s_and_b64 s[14:15], s[16:17], s[14:15]
	v_cmp_gt_i32_e64 s[10:11], 8, v0
	s_and_b64 s[12:13], s[14:15], s[12:13]
	v_cmp_gt_i32_e64 s[8:9], 3, v0
	s_and_b64 s[10:11], s[12:13], s[10:11]
	v_cmp_gt_i32_e64 s[4:5], 2, v0
	s_and_b64 s[8:9], s[10:11], s[8:9]
	v_cmp_gt_i32_e64 s[2:3], 1, v0
	s_and_b64 s[4:5], s[8:9], s[4:5]
	v_cmp_gt_i32_e32 vcc, 0, v0
	s_and_b64 s[2:3], s[4:5], s[2:3]
	s_and_b64 vcc, s[2:3], vcc
	v_cndmask_b32_e64 v95, v95, v244, s[34:35]
	v_cndmask_b32_e64 v94, v94, v244, s[30:31]
	v_cndmask_b32_e64 v93, v93, v244, s[28:29]
	v_cndmask_b32_e64 v92, v92, v244, s[26:27]
	v_cndmask_b32_e64 v91, v91, v244, s[24:25]
	v_cndmask_b32_e64 v90, v90, v244, s[22:23]
	v_cndmask_b32_e64 v89, v89, v244, s[20:21]
	v_cndmask_b32_e64 v88, v88, v244, s[18:19]
	v_cndmask_b32_e64 v87, v87, v244, s[16:17]
	v_cndmask_b32_e64 v86, v86, v244, s[14:15]
	v_cndmask_b32_e64 v85, v85, v244, s[12:13]
	v_cndmask_b32_e64 v84, v84, v244, s[10:11]
	v_cndmask_b32_e64 v83, v83, v244, s[8:9]
	v_cndmask_b32_e64 v82, v82, v244, s[4:5]
	v_cndmask_b32_e64 v81, v81, v244, s[2:3]
	v_cndmask_b32_e32 v80, v80, v244, vcc

.LBB0_649:
	v_sub_f32_e32 v3, v80, v2
	v_exp_f32_e32 v3, v3
	v_sub_f32_e32 v4, v81, v2
	v_exp_f32_e32 v4, v4
	v_sub_f32_e32 v5, v82, v2
	v_exp_f32_e32 v5, v5
	v_sub_f32_e32 v6, v83, v2
	v_exp_f32_e32 v6, v6
	v_sub_f32_e32 v8, v84, v2
	v_add_f32_e32 v7, 0, v3
	v_exp_f32_e32 v8, v8
	v_sub_f32_e32 v9, v85, v2
	v_add_f32_e32 v7, v4, v7
	v_exp_f32_e32 v9, v9
	v_sub_f32_e32 v10, v86, v2
	v_add_f32_e32 v7, v5, v7
	v_exp_f32_e32 v10, v10
	v_sub_f32_e32 v11, v87, v2
	v_add_f32_e32 v7, v6, v7
	v_exp_f32_e32 v11, v11
	v_sub_f32_e32 v12, v88, v2
	v_add_f32_e32 v7, v8, v7
	v_exp_f32_e32 v12, v12
	v_sub_f32_e32 v13, v89, v2
	v_add_f32_e32 v7, v9, v7
	v_exp_f32_e32 v13, v13
	v_sub_f32_e32 v14, v90, v2
	v_add_f32_e32 v7, v10, v7
	v_exp_f32_e32 v14, v14
	v_sub_f32_e32 v15, v91, v2
	v_add_f32_e32 v7, v11, v7
	v_exp_f32_e32 v15, v15
	v_sub_f32_e32 v80, v92, v2
	v_add_f32_e32 v7, v12, v7
	v_exp_f32_e32 v80, v80
	v_sub_f32_e32 v81, v93, v2
	v_add_f32_e32 v7, v13, v7
	v_exp_f32_e32 v81, v81
	v_sub_f32_e32 v82, v94, v2
	v_add_f32_e32 v7, v14, v7
	v_exp_f32_e32 v82, v82
	v_sub_f32_e32 v83, v95, v2
	v_add_f32_e32 v7, v15, v7
	v_exp_f32_e32 v83, v83
	v_add_f32_e32 v7, v80, v7
	v_add_f32_e32 v7, v81, v7
	v_add_f32_e32 v7, v82, v7
	v_add_f32_e32 v84, v83, v7
	v_fmac_f32_e32 v84, v212, v0
	v_cvt_pk_bf16_f32 v4, v3, v4
	v_cvt_pk_bf16_f32 v5, v5, v6
	v_cvt_pk_bf16_f32 v6, v8, v9
	v_cvt_pk_bf16_f32 v7, v10, v11
	v_cvt_pk_bf16_f32 v8, v12, v13
	v_cvt_pk_bf16_f32 v9, v14, v15
	v_cvt_pk_bf16_f32 v10, v80, v81
	v_cvt_pk_bf16_f32 v11, v82, v83
	s_setprio 1
	v_add_u32_e32 v0, v223, v222
	ds_read_b64 v[12:13], v0 offset:25600
	ds_read_b64 v[14:15], v0 offset:25616
	ds_read_b64 v[230:231], v0 offset:25632
	ds_read_b64 v[232:233], v0 offset:25648
	ds_read_b64 v[234:235], v0 offset:30208
	ds_read_b64 v[236:237], v0 offset:30224
	ds_read_b64 v[246:247], v0 offset:30240
	ds_read_b64 v[248:249], v0 offset:30256
	ds_read_b64 v[250:251], v0 offset:34816
	ds_read_b64 v[252:253], v0 offset:34832
	s_waitcnt lgkmcnt(8)
	v_mfma_f32_32x32x16_bf16 v[64:79], v[12:15], v[4:7], v[64:79]
	ds_read_b64 v[12:13], v0 offset:34848
	ds_read_b64 v[14:15], v0 offset:34864
	s_waitcnt lgkmcnt(8)
	v_mfma_f32_32x32x16_bf16 v[64:79], v[230:233], v[8:11], v[64:79]
	ds_read_b64 v[230:231], v0 offset:39424
	ds_read_b64 v[232:233], v0 offset:39440
	s_waitcnt lgkmcnt(8)
	v_mfma_f32_32x32x16_bf16 v[48:63], v[234:237], v[4:7], v[48:63]
	ds_read_b64 v[234:235], v0 offset:39456
	ds_read_b64 v[236:237], v0 offset:39472
	s_waitcnt lgkmcnt(8)
	v_mfma_f32_32x32x16_bf16 v[48:63], v[246:249], v[8:11], v[48:63]
	s_waitcnt lgkmcnt(6)
	v_mfma_f32_32x32x16_bf16 v[32:47], v[250:253], v[4:7], v[32:47]
	s_waitcnt lgkmcnt(4)
	v_mfma_f32_32x32x16_bf16 v[32:47], v[12:15], v[8:11], v[32:47]
	s_waitcnt lgkmcnt(2)
	v_mfma_f32_32x32x16_bf16 v[16:31], v[230:233], v[4:7], v[16:31]
	s_waitcnt lgkmcnt(0)
	v_mfma_f32_32x32x16_bf16 v[16:31], v[234:237], v[8:11], v[16:31]
	s_setprio 0
	v_mov_b32_e32 v229, v2
	v_mov_b32_e32 v212, v84
; #define AT_LOAD(RK, RV, T) { const size_t ko_ = (size_t)(T) * 64 * 192; const int vo_ = (T) * 64; \
;     _Pragma("unroll") for (int i = 0; i < 3; ++i) { const int id = tid + NT * i, row = id / 24, cc = id % 24; RK[i] = *(const u32x4*)(Kg + ko_ + row * 192 + cc * 8); } \
;     _Pragma("unroll") for (int i = 0; i < 2; ++i) RV[i] = *(const u32x4*)(Vg + (size_t)(vrow + 64 * i) * S_ + vo_ + vcc * 8); }
; #define AT_WRITE(RK, RV, ST) { char* dK = smem + (ST) * STG; \
;     _Pragma("unroll") for (int i = 0; i < 3; ++i) { const int id = tid + NT * i, row = id / 24, cc = id % 24; *(u32x4*)(dK + row * 400 + cc * 16) = RK[i]; } \
;     _Pragma("unroll") for (int i = 0; i < 2; ++i) *(u32x4*)(dK + KST + (vrow + 64 * i) * 144 + vcc * 16) = RV[i]; }
; DI void mla_attn_item(const Params& P, int hd, int b, char* smem) {
;     ...
;     AT_WRITE(rk0, rv0, 0);
;     AT_LOAD(rk0, rv0, (kt + 4 < ntl ? kt + 4 : ntl));
;     AT_COMPUTE(1, kt + 1);
.LBB0_650:
	s_or_b64 exec, exec, s[38:39]
	s_add_i32 s2, s60, 6
	s_min_u32 s2, s2, s57
	s_mul_i32 s62, s2, 0x6000
	v_lshl_add_u64 v[2:3], v[188:189], 0, s[62:63]
	v_lshl_add_u64 v[4:5], v[190:191], 1, v[2:3]
	s_waitcnt lgkmcnt(0)
	s_barrier
	ds_write_b128 v217, v[156:159]
	ds_write_b128 v218, v[160:163]
	ds_write_b128 v219, v[164:167]
	ds_write_b128 v220, v[168:171] offset:25600
	ds_write_b128 v220, v[172:175] offset:34816
	v_lshl_add_u64 v[4:5], v[192:193], 1, v[4:5]
	v_lshl_add_u64 v[6:7], v[194:195], 1, v[2:3]
	v_lshl_add_u64 v[2:3], v[198:199], 1, v[2:3]
	s_lshl_b32 s62, s2, 7
	v_lshl_add_u64 v[6:7], v[196:197], 1, v[6:7]
	flat_load_dwordx4 v[156:159], v[4:5]
	flat_load_dwordx4 v[160:163], v[6:7]
	v_lshl_add_u64 v[2:3], v[200:201], 1, v[2:3]
	v_lshl_add_u64 v[4:5], v[202:203], 0, s[62:63]
	v_lshl_add_u64 v[6:7], v[4:5], 0, v[204:205]
	flat_load_dwordx4 v[164:167], v[2:3]
	flat_load_dwordx4 v[168:171], v[6:7]
	v_lshl_add_u64 v[2:3], v[4:5], 0, v[210:211]
	flat_load_dwordx4 v[172:175], v[2:3]
	v_subrev_u32_e32 v0, 31, v224
	v_cmp_le_i32_e32 vcc, v0, v213
	s_and_saveexec_b64 s[38:39], vcc
	s_cbranch_execz .LBB0_643
	s_setprio 1
	ds_read_b128 v[2:5], v228 offset:44032
	ds_read_b128 v[230:233], v228 offset:44064
	ds_read_b128 v[234:237], v228 offset:44096
	ds_read_b128 v[246:249], v228 offset:44128
	ds_read_b128 v[250:253], v228 offset:44160
	s_waitcnt lgkmcnt(4)
	v_mfma_f32_32x32x16_bf16 v[80:95], v[2:5], v[96:99], 0
	ds_read_b128 v[2:5], v228 offset:44192
	s_waitcnt lgkmcnt(4)
	v_mfma_f32_32x32x16_bf16 v[80:95], v[230:233], v[100:103], v[80:95]
	ds_read_b128 v[230:233], v228 offset:44224
	s_waitcnt lgkmcnt(4)
	v_mfma_f32_32x32x16_bf16 v[80:95], v[234:237], v[104:107], v[80:95]
	ds_read_b128 v[234:237], v228 offset:44256
	s_waitcnt lgkmcnt(4)
	v_mfma_f32_32x32x16_bf16 v[80:95], v[246:249], v[108:111], v[80:95]
	ds_read_b128 v[246:249], v228 offset:44288
	s_waitcnt lgkmcnt(4)
	v_mfma_f32_32x32x16_bf16 v[80:95], v[250:253], v[112:115], v[80:95]
	ds_read_b128 v[250:253], v228 offset:44320
	s_waitcnt lgkmcnt(4)
	v_mfma_f32_32x32x16_bf16 v[80:95], v[2:5], v[116:119], v[80:95]
	ds_read_b128 v[2:5], v228 offset:44352
	s_waitcnt lgkmcnt(4)
	v_mfma_f32_32x32x16_bf16 v[80:95], v[230:233], v[120:123], v[80:95]
	ds_read_b128 v[230:233], v228 offset:44384
	s_waitcnt lgkmcnt(4)
	v_mfma_f32_32x32x16_bf16 v[80:95], v[234:237], v[124:127], v[80:95]
	s_waitcnt lgkmcnt(3)
	v_mfma_f32_32x32x16_bf16 v[80:95], v[246:249], v[128:131], v[80:95]
	s_waitcnt lgkmcnt(2)
	v_mfma_f32_32x32x16_bf16 v[80:95], v[250:253], v[176:179], v[80:95]
	s_waitcnt lgkmcnt(1)
	v_mfma_f32_32x32x16_bf16 v[80:95], v[2:5], v[132:135], v[80:95]
	s_waitcnt lgkmcnt(0)
	v_mfma_f32_32x32x16_bf16 v[80:95], v[230:233], v[180:183], v[80:95]
	s_setprio 0
	v_cmp_gt_i32_e32 vcc, v224, v213
	s_and_saveexec_b64 s[78:79], vcc
	s_cbranch_execz .LBB0_653
	v_mov_b32_e32 v0, v225
	s_nop 0
	v_cmp_gt_i32_e64 s[30:31], 26, v0
	v_cmp_gt_i32_e64 s[34:35], 27, v0
	v_cmp_gt_i32_e64 s[28:29], 25, v0
	s_and_b64 s[30:31], s[34:35], s[30:31]
	v_cmp_gt_i32_e64 s[26:27], 24, v0
	s_and_b64 s[28:29], s[30:31], s[28:29]
	v_cmp_gt_i32_e64 s[24:25], 19, v0
	s_and_b64 s[26:27], s[28:29], s[26:27]
	v_cmp_gt_i32_e64 s[22:23], 18, v0
	s_and_b64 s[24:25], s[26:27], s[24:25]
	v_cmp_gt_i32_e64 s[20:21], 17, v0
	s_and_b64 s[22:23], s[24:25], s[22:23]
	v_cmp_gt_i32_e64 s[18:19], 16, v0
	s_and_b64 s[20:21], s[22:23], s[20:21]
	v_cmp_gt_i32_e64 s[16:17], 11, v0
	s_and_b64 s[18:19], s[20:21], s[18:19]
	v_cmp_gt_i32_e64 s[14:15], 10, v0
	s_and_b64 s[16:17], s[18:19], s[16:17]
	v_cmp_gt_i32_e64 s[12:13], 9, v0
	s_and_b64 s[14:15], s[16:17], s[14:15]
	v_cmp_gt_i32_e64 s[10:11], 8, v0
	s_and_b64 s[12:13], s[14:15], s[12:13]
	v_cmp_gt_i32_e64 s[8:9], 3, v0
	s_and_b64 s[10:11], s[12:13], s[10:11]
	v_cmp_gt_i32_e64 s[4:5], 2, v0
	s_and_b64 s[8:9], s[10:11], s[8:9]
	v_cmp_gt_i32_e64 s[2:3], 1, v0
	s_and_b64 s[4:5], s[8:9], s[4:5]
	v_cmp_gt_i32_e32 vcc, 0, v0
	s_and_b64 s[2:3], s[4:5], s[2:3]
	s_and_b64 vcc, s[2:3], vcc
	v_cndmask_b32_e64 v95, v95, v244, s[34:35]
	v_cndmask_b32_e64 v94, v94, v244, s[30:31]
	v_cndmask_b32_e64 v93, v93, v244, s[28:29]
	v_cndmask_b32_e64 v92, v92, v244, s[26:27]
	v_cndmask_b32_e64 v91, v91, v244, s[24:25]
	v_cndmask_b32_e64 v90, v90, v244, s[22:23]
	v_cndmask_b32_e64 v89, v89, v244, s[20:21]
	v_cndmask_b32_e64 v88, v88, v244, s[18:19]
	v_cndmask_b32_e64 v87, v87, v244, s[16:17]
	v_cndmask_b32_e64 v86, v86, v244, s[14:15]
	v_cndmask_b32_e64 v85, v85, v244, s[12:13]
	v_cndmask_b32_e64 v84, v84, v244, s[10:11]
	v_cndmask_b32_e64 v83, v83, v244, s[8:9]
	v_cndmask_b32_e64 v82, v82, v244, s[4:5]
	v_cndmask_b32_e64 v81, v81, v244, s[2:3]
	v_cndmask_b32_e32 v80, v80, v244, vcc
